# nt hint also on the read-once f32 residual (x) loads of the first W_out epilogue
# speedup vs baseline: 1.1384x; 1.0900x over previous
.LBB0_240:
	s_andn2_b64 vcc, exec, s[50:51]
	v_mov_b32_e32 v195, 0
	s_cbranch_vccnz .LBB0_245
	v_add_u32_e32 v150, s10, v146
	s_andn2_b64 vcc, exec, s[38:39]
	v_ashrrev_i32_e32 v151, 31, v150
	s_cbranch_vccnz .LBB0_1270
	v_lshl_add_u64 v[122:123], v[150:151], 2, v[174:175]
	global_load_dwordx4 v[126:129], v[122:123], off offset:16 nt
	s_nop 0
	global_load_dwordx4 v[122:125], v[122:123], off nt
	v_lshl_add_u64 v[150:151], v[150:151], 1, v[170:171]
	s_cbranch_execnz .LBB0_244

.LBB0_297:
	s_andn2_b64 vcc, exec, s[50:51]
	v_mov_b32_e32 v114, v195
	s_cbranch_vccnz .LBB0_302
	v_add_u32_e32 v182, s10, v122
	s_andn2_b64 vcc, exec, s[38:39]
	v_ashrrev_i32_e32 v183, 31, v182
	s_cbranch_vccnz .LBB0_1272
	v_lshl_add_u64 v[114:115], v[182:183], 2, v[174:175]
	global_load_dwordx4 v[118:121], v[114:115], off offset:16 nt
	s_nop 0
	global_load_dwordx4 v[114:117], v[114:115], off nt
	v_lshl_add_u64 v[170:171], v[182:183], 1, v[170:171]
	s_cbranch_execnz .LBB0_301

.LBB0_370:
	s_andn2_b64 vcc, exec, s[50:51]
	v_mov_b32_e32 v180, 0
	s_cbranch_vccnz .LBB0_375
	v_add_u32_e32 v120, s10, v146
	s_andn2_b64 vcc, exec, s[38:39]
	v_ashrrev_i32_e32 v121, 31, v120
	s_cbranch_vccnz .LBB0_1273
	v_lshl_add_u64 v[106:107], v[120:121], 2, v[168:169]
	global_load_dwordx4 v[110:113], v[106:107], off offset:16 nt
	s_nop 0
	global_load_dwordx4 v[106:109], v[106:107], off nt
	v_lshl_add_u64 v[120:121], v[120:121], 1, v[160:161]
	s_cbranch_execnz .LBB0_374

.LBB0_429:
	s_andn2_b64 vcc, exec, s[50:51]
	v_mov_b32_e32 v98, v180
	s_cbranch_vccnz .LBB0_434
	v_add_u32_e32 v170, s10, v122
	s_andn2_b64 vcc, exec, s[38:39]
	v_ashrrev_i32_e32 v171, 31, v170
	s_cbranch_vccnz .LBB0_1275
	v_lshl_add_u64 v[98:99], v[170:171], 2, v[168:169]
	global_load_dwordx4 v[102:105], v[98:99], off offset:16 nt
	s_nop 0
	global_load_dwordx4 v[98:101], v[98:99], off nt
	v_lshl_add_u64 v[160:161], v[170:171], 1, v[160:161]
	s_cbranch_execnz .LBB0_433

.LBB0_497:
	s_andn2_b64 vcc, exec, s[50:51]
	v_mov_b32_e32 v164, 0
	s_cbranch_vccnz .LBB0_502
	v_add_u32_e32 v102, s10, v146
	s_andn2_b64 vcc, exec, s[38:39]
	v_ashrrev_i32_e32 v103, 31, v102
	s_cbranch_vccnz .LBB0_1276
	v_lshl_add_u64 v[90:91], v[102:103], 2, v[152:153]
	global_load_dwordx4 v[94:97], v[90:91], off offset:16 nt
	s_nop 0
	global_load_dwordx4 v[90:93], v[90:91], off nt
	v_lshl_add_u64 v[102:103], v[102:103], 1, v[118:119]
	s_cbranch_execnz .LBB0_501

.LBB0_559:
	s_andn2_b64 vcc, exec, s[50:51]
	v_mov_b32_e32 v82, v164
	s_cbranch_vccnz .LBB0_564
	v_add_u32_e32 v154, s10, v122
	s_andn2_b64 vcc, exec, s[38:39]
	v_ashrrev_i32_e32 v155, 31, v154
	s_cbranch_vccnz .LBB0_1278
	v_lshl_add_u64 v[82:83], v[154:155], 2, v[152:153]
	global_load_dwordx4 v[86:89], v[82:83], off offset:16 nt
	s_nop 0
	global_load_dwordx4 v[82:85], v[82:83], off nt
	v_lshl_add_u64 v[118:119], v[154:155], 1, v[118:119]
	s_cbranch_execnz .LBB0_563

.LBB0_627:
	s_andn2_b64 vcc, exec, s[50:51]
	v_mov_b32_e32 v124, 0
	s_cbranch_vccnz .LBB0_632
	v_add_u32_e32 v86, s10, v146
	s_andn2_b64 vcc, exec, s[38:39]
	v_ashrrev_i32_e32 v87, 31, v86
	s_cbranch_vccnz .LBB0_1279
	v_lshl_add_u64 v[74:75], v[86:87], 2, v[108:109]
	global_load_dwordx4 v[78:81], v[74:75], off offset:16 nt
	s_nop 0
	global_load_dwordx4 v[74:77], v[74:75], off nt
	v_lshl_add_u64 v[86:87], v[86:87], 1, v[100:101]
	s_cbranch_execnz .LBB0_631

.LBB0_689:
	s_andn2_b64 vcc, exec, s[50:51]
	v_mov_b32_e32 v66, v124
	s_cbranch_vccnz .LBB0_694
	v_add_u32_e32 v110, s10, v122
	s_andn2_b64 vcc, exec, s[38:39]
	v_ashrrev_i32_e32 v111, 31, v110
	s_cbranch_vccnz .LBB0_1281
	v_lshl_add_u64 v[66:67], v[110:111], 2, v[108:109]
	global_load_dwordx4 v[70:73], v[66:67], off offset:16 nt
	s_nop 0
	global_load_dwordx4 v[66:69], v[66:67], off nt
	v_lshl_add_u64 v[100:101], v[110:111], 1, v[100:101]
	s_cbranch_execnz .LBB0_693

.LBB0_757:
	s_andn2_b64 vcc, exec, s[50:51]
	v_mov_b32_e32 v104, 0
	s_cbranch_vccnz .LBB0_762
	v_add_u32_e32 v70, s10, v146
	s_andn2_b64 vcc, exec, s[38:39]
	v_ashrrev_i32_e32 v71, 31, v70
	s_cbranch_vccnz .LBB0_1282
	v_lshl_add_u64 v[58:59], v[70:71], 2, v[92:93]
	global_load_dwordx4 v[62:65], v[58:59], off offset:16 nt
	s_nop 0
	global_load_dwordx4 v[58:61], v[58:59], off nt
	v_lshl_add_u64 v[70:71], v[70:71], 1, v[84:85]
	s_cbranch_execnz .LBB0_761

.LBB0_819:
	s_andn2_b64 vcc, exec, s[50:51]
	v_mov_b32_e32 v50, v104
	s_cbranch_vccnz .LBB0_824
	v_add_u32_e32 v94, s10, v122
	s_andn2_b64 vcc, exec, s[38:39]
	v_ashrrev_i32_e32 v95, 31, v94
	s_cbranch_vccnz .LBB0_1284
	v_lshl_add_u64 v[50:51], v[94:95], 2, v[92:93]
	global_load_dwordx4 v[54:57], v[50:51], off offset:16 nt
	s_nop 0
	global_load_dwordx4 v[50:53], v[50:51], off nt
	v_lshl_add_u64 v[84:85], v[94:95], 1, v[84:85]
	s_cbranch_execnz .LBB0_823

.LBB0_887:
	s_andn2_b64 vcc, exec, s[50:51]
	v_mov_b32_e32 v88, 0
	s_cbranch_vccnz .LBB0_892
	v_add_u32_e32 v54, s10, v146
	s_andn2_b64 vcc, exec, s[38:39]
	v_ashrrev_i32_e32 v55, 31, v54
	s_cbranch_vccnz .LBB0_1285
	v_lshl_add_u64 v[42:43], v[54:55], 2, v[76:77]
	global_load_dwordx4 v[46:49], v[42:43], off offset:16 nt
	s_nop 0
	global_load_dwordx4 v[42:45], v[42:43], off nt
	v_lshl_add_u64 v[54:55], v[54:55], 1, v[68:69]
	s_cbranch_execnz .LBB0_891

.LBB0_949:
	s_andn2_b64 vcc, exec, s[50:51]
	v_mov_b32_e32 v34, v88
	s_cbranch_vccnz .LBB0_954
	v_add_u32_e32 v78, s10, v122
	s_andn2_b64 vcc, exec, s[38:39]
	v_ashrrev_i32_e32 v79, 31, v78
	s_cbranch_vccnz .LBB0_1287
	v_lshl_add_u64 v[34:35], v[78:79], 2, v[76:77]
	global_load_dwordx4 v[38:41], v[34:35], off offset:16 nt
	s_nop 0
	global_load_dwordx4 v[34:37], v[34:35], off nt
	v_lshl_add_u64 v[68:69], v[78:79], 1, v[68:69]
	s_cbranch_execnz .LBB0_953

.LBB0_1017:
	s_andn2_b64 vcc, exec, s[50:51]
	v_mov_b32_e32 v72, 0
	s_cbranch_vccnz .LBB0_1022
	v_add_u32_e32 v38, s10, v146
	s_andn2_b64 vcc, exec, s[38:39]
	v_ashrrev_i32_e32 v39, 31, v38
	s_cbranch_vccnz .LBB0_1288
	v_lshl_add_u64 v[26:27], v[38:39], 2, v[60:61]
	global_load_dwordx4 v[30:33], v[26:27], off offset:16 nt
	s_nop 0
	global_load_dwordx4 v[26:29], v[26:27], off nt
	v_lshl_add_u64 v[38:39], v[38:39], 1, v[52:53]
	s_cbranch_execnz .LBB0_1021

.LBB0_1079:
	s_andn2_b64 vcc, exec, s[50:51]
	v_mov_b32_e32 v18, v72
	s_cbranch_vccnz .LBB0_1084
	v_add_u32_e32 v62, s10, v122
	s_andn2_b64 vcc, exec, s[38:39]
	v_ashrrev_i32_e32 v63, 31, v62
	s_cbranch_vccnz .LBB0_1290
	v_lshl_add_u64 v[18:19], v[62:63], 2, v[60:61]
	global_load_dwordx4 v[22:25], v[18:19], off offset:16 nt
	s_nop 0
	global_load_dwordx4 v[18:21], v[18:19], off nt
	v_lshl_add_u64 v[52:53], v[62:63], 1, v[52:53]
	s_cbranch_execnz .LBB0_1083

.LBB0_1147:
	s_andn2_b64 vcc, exec, s[28:29]
	v_mov_b32_e32 v56, 0
	s_cbranch_vccnz .LBB0_1152
	v_add_u32_e32 v22, s10, v146
	s_andn2_b64 vcc, exec, s[38:39]
	v_ashrrev_i32_e32 v23, 31, v22
	s_cbranch_vccnz .LBB0_1291
	v_lshl_add_u64 v[10:11], v[22:23], 2, v[44:45]
	global_load_dwordx4 v[14:17], v[10:11], off offset:16 nt
	s_nop 0
	global_load_dwordx4 v[10:13], v[10:11], off nt
	v_lshl_add_u64 v[22:23], v[22:23], 1, v[36:37]
	s_cbranch_execnz .LBB0_1151

.LBB0_1210:
	s_andn2_b64 vcc, exec, s[20:21]
	v_mov_b32_e32 v2, v56
	s_cbranch_vccnz .LBB0_1215
	v_add_u32_e32 v46, s10, v122
	s_andn2_b64 vcc, exec, s[38:39]
	v_ashrrev_i32_e32 v47, 31, v46
	s_cbranch_vccnz .LBB0_1293
	v_lshl_add_u64 v[2:3], v[46:47], 2, v[44:45]
	global_load_dwordx4 v[6:9], v[2:3], off offset:16 nt
	s_nop 0
	global_load_dwordx4 v[2:5], v[2:3], off nt
	v_lshl_add_u64 v[36:37], v[46:47], 1, v[36:37]
	s_cbranch_execnz .LBB0_1214
